# Fourier stage-1 hand-off published with sc1 write-through stores instead of plain stores plus an L2 write-back fence per workgroup
# speedup vs baseline: 1.0037x; 1.0037x over previous
.Ldq_skip2:
	s_mov_b64 exec, s[8:9]
	s_mov_b32 s99, 1
	ds_read_b128 v[72:75], v16
	ds_read_b128 v[76:79], v16 offset:2048
	ds_read_b128 v[106:109], v16 offset:4096
	ds_read_b128 v[112:115], v16 offset:6144
	ds_read_b128 v[116:119], v17
	ds_read_b128 v[120:123], v17 offset:2048
	ds_read_b128 v[124:127], v17 offset:4096
	ds_read_b128 v[128:131], v17 offset:6144
	s_waitcnt lgkmcnt(8)
	v_mfma_f32_16x16x32_bf16 v[84:87], v[152:155], v[102:105], v[84:87]
	v_mfma_f32_16x16x32_bf16 v[88:91], v[156:159], v[102:105], v[88:91]
	v_mfma_f32_16x16x32_bf16 v[92:95], v[160:163], v[102:105], v[92:95]
	v_mfma_f32_16x16x32_bf16 v[22:25], v[164:167], v[102:105], v[22:25]
	v_mfma_f32_16x16x32_bf16 v[38:41], v[152:155], v[132:135], v[38:41]
	v_mfma_f32_16x16x32_bf16 v[46:49], v[156:159], v[132:135], v[46:49]
	v_mfma_f32_16x16x32_bf16 v[58:61], v[160:163], v[132:135], v[58:61]
	v_mfma_f32_16x16x32_bf16 v[50:53], v[164:167], v[132:135], v[50:53]
	v_mfma_f32_16x16x32_bf16 v[42:45], v[152:155], v[138:141], v[42:45]
	v_mfma_f32_16x16x32_bf16 v[62:65], v[156:159], v[138:141], v[62:65]
	v_mfma_f32_16x16x32_bf16 v[66:69], v[160:163], v[138:141], v[66:69]
	v_mfma_f32_16x16x32_bf16 v[54:57], v[164:167], v[138:141], v[54:57]
	v_mfma_f32_16x16x32_bf16 v[34:37], v[152:155], v[142:145], v[34:37]
	v_mfma_f32_16x16x32_bf16 v[30:33], v[156:159], v[142:145], v[30:33]
	v_mfma_f32_16x16x32_bf16 v[26:29], v[160:163], v[142:145], v[26:29]
	v_mfma_f32_16x16x32_bf16 v[18:21], v[164:167], v[142:145], v[18:21]
	s_waitcnt vmcnt(6) lgkmcnt(0)
	s_barrier
	ds_read_b128 v[102:105], v8
	ds_read_b128 v[132:135], v8 offset:2048
	ds_read_b128 v[138:141], v8 offset:4096
	ds_read_b128 v[142:145], v8 offset:6144
	ds_read_b128 v[152:155], v9 offset:16384
	ds_read_b128 v[156:159], v9 offset:18432
	ds_read_b128 v[160:163], v9 offset:20480
	ds_read_b128 v[164:167], v9 offset:22528
	v_mfma_f32_16x16x32_bf16 v[84:87], v[116:119], v[72:75], v[84:87]
	v_mfma_f32_16x16x32_bf16 v[88:91], v[120:123], v[72:75], v[88:91]
	v_mfma_f32_16x16x32_bf16 v[92:95], v[124:127], v[72:75], v[92:95]
	v_mfma_f32_16x16x32_bf16 v[22:25], v[128:131], v[72:75], v[22:25]
	v_mfma_f32_16x16x32_bf16 v[38:41], v[116:119], v[76:79], v[38:41]
	v_mfma_f32_16x16x32_bf16 v[46:49], v[120:123], v[76:79], v[46:49]
	v_mfma_f32_16x16x32_bf16 v[58:61], v[124:127], v[76:79], v[58:61]
	v_mfma_f32_16x16x32_bf16 v[50:53], v[128:131], v[76:79], v[50:53]
	v_mfma_f32_16x16x32_bf16 v[42:45], v[116:119], v[106:109], v[42:45]
	v_mfma_f32_16x16x32_bf16 v[62:65], v[120:123], v[106:109], v[62:65]
	v_mfma_f32_16x16x32_bf16 v[66:69], v[124:127], v[106:109], v[66:69]
	v_mfma_f32_16x16x32_bf16 v[54:57], v[128:131], v[106:109], v[54:57]
	v_mfma_f32_16x16x32_bf16 v[34:37], v[116:119], v[112:115], v[34:37]
	v_mfma_f32_16x16x32_bf16 v[30:33], v[120:123], v[112:115], v[30:33]
	v_mfma_f32_16x16x32_bf16 v[26:29], v[124:127], v[112:115], v[26:29]
	v_mfma_f32_16x16x32_bf16 v[18:21], v[128:131], v[112:115], v[18:21]
	s_mov_b64 s[8:9], 0x700
	s_mov_b32 m0, s64
	v_lshl_add_u64 v[72:73], v[2:3], 0, s[8:9]
	global_load_lds_dwordx4 v[72:73], off
	v_lshl_add_u64 v[72:73], v[4:5], 0, s[8:9]
	s_mov_b32 m0, s71
	s_nop 0
	global_load_lds_dwordx4 v[72:73], off
	v_lshl_add_u64 v[72:73], v[6:7], 0, s[8:9]
	s_mov_b32 m0, s73
	s_mov_b64 s[8:9], 0x20700
	global_load_lds_dwordx4 v[72:73], off
	v_lshl_add_u64 v[72:73], v[6:7], 0, s[8:9]
	s_mov_b32 m0, s74
	s_mov_b64 s[8:9], 0x40700
	global_load_lds_dwordx4 v[72:73], off
	v_lshl_add_u64 v[72:73], v[6:7], 0, s[8:9]
	s_mov_b32 m0, s75
	s_mov_b64 s[8:9], 0x60700
	global_load_lds_dwordx4 v[72:73], off
	v_lshl_add_u64 v[72:73], v[6:7], 0, s[8:9]
	s_mov_b32 m0, s76
	s_nop 0
	global_load_lds_dwordx4 v[72:73], off
	ds_read_b128 v[72:75], v10
	ds_read_b128 v[76:79], v10 offset:2048
	ds_read_b128 v[106:109], v10 offset:4096
	ds_read_b128 v[112:115], v10 offset:6144
	ds_read_b128 v[116:119], v11 offset:16384
	ds_read_b128 v[120:123], v11 offset:18432
	ds_read_b128 v[124:127], v11 offset:20480
	ds_read_b128 v[128:131], v11 offset:22528
	s_waitcnt lgkmcnt(8)
	v_mfma_f32_16x16x32_bf16 v[84:87], v[152:155], v[102:105], v[84:87]
	v_mfma_f32_16x16x32_bf16 v[88:91], v[156:159], v[102:105], v[88:91]
	v_mfma_f32_16x16x32_bf16 v[92:95], v[160:163], v[102:105], v[92:95]
	v_mfma_f32_16x16x32_bf16 v[22:25], v[164:167], v[102:105], v[22:25]
	v_mfma_f32_16x16x32_bf16 v[38:41], v[152:155], v[132:135], v[38:41]
	v_mfma_f32_16x16x32_bf16 v[46:49], v[156:159], v[132:135], v[46:49]
	v_mfma_f32_16x16x32_bf16 v[58:61], v[160:163], v[132:135], v[58:61]
	v_mfma_f32_16x16x32_bf16 v[50:53], v[164:167], v[132:135], v[50:53]
	v_mfma_f32_16x16x32_bf16 v[42:45], v[152:155], v[138:141], v[42:45]
	v_mfma_f32_16x16x32_bf16 v[62:65], v[156:159], v[138:141], v[62:65]
	v_mfma_f32_16x16x32_bf16 v[66:69], v[160:163], v[138:141], v[66:69]
	v_mfma_f32_16x16x32_bf16 v[54:57], v[164:167], v[138:141], v[54:57]
	v_mfma_f32_16x16x32_bf16 v[34:37], v[152:155], v[142:145], v[34:37]
	v_mfma_f32_16x16x32_bf16 v[30:33], v[156:159], v[142:145], v[30:33]
	v_mfma_f32_16x16x32_bf16 v[26:29], v[160:163], v[142:145], v[26:29]
	v_mfma_f32_16x16x32_bf16 v[18:21], v[164:167], v[142:145], v[18:21]
	s_waitcnt vmcnt(6) lgkmcnt(0)
	s_barrier
	ds_read_b128 v[102:105], v8 offset:49152
	ds_read_b128 v[132:135], v8 offset:51200
	ds_read_b128 v[138:141], v8 offset:53248
	ds_read_b128 v[142:145], v8 offset:55296
	ds_read_b128 v[152:155], v12
	ds_read_b128 v[156:159], v12 offset:2048
	ds_read_b128 v[160:163], v12 offset:4096
	ds_read_b128 v[164:167], v12 offset:6144
	v_mfma_f32_16x16x32_bf16 v[84:87], v[116:119], v[72:75], v[84:87]
	v_mfma_f32_16x16x32_bf16 v[88:91], v[120:123], v[72:75], v[88:91]
	v_mfma_f32_16x16x32_bf16 v[92:95], v[124:127], v[72:75], v[92:95]
	v_mfma_f32_16x16x32_bf16 v[22:25], v[128:131], v[72:75], v[22:25]
	v_mfma_f32_16x16x32_bf16 v[38:41], v[116:119], v[76:79], v[38:41]
	v_mfma_f32_16x16x32_bf16 v[46:49], v[120:123], v[76:79], v[46:49]
	v_mfma_f32_16x16x32_bf16 v[58:61], v[124:127], v[76:79], v[58:61]
	v_mfma_f32_16x16x32_bf16 v[50:53], v[128:131], v[76:79], v[50:53]
	v_mfma_f32_16x16x32_bf16 v[42:45], v[116:119], v[106:109], v[42:45]
	v_mfma_f32_16x16x32_bf16 v[62:65], v[120:123], v[106:109], v[62:65]
	v_mfma_f32_16x16x32_bf16 v[66:69], v[124:127], v[106:109], v[66:69]
	v_mfma_f32_16x16x32_bf16 v[54:57], v[128:131], v[106:109], v[54:57]
	v_mfma_f32_16x16x32_bf16 v[34:37], v[116:119], v[112:115], v[34:37]
	v_mfma_f32_16x16x32_bf16 v[30:33], v[120:123], v[112:115], v[30:33]
	v_mfma_f32_16x16x32_bf16 v[26:29], v[124:127], v[112:115], v[26:29]
	v_mfma_f32_16x16x32_bf16 v[18:21], v[128:131], v[112:115], v[18:21]
	s_mov_b64 s[8:9], 0x780
	s_mov_b32 m0, s57
	v_lshl_add_u64 v[2:3], v[2:3], 0, s[8:9]
	global_load_lds_dwordx4 v[2:3], off
	v_lshl_add_u64 v[2:3], v[4:5], 0, s[8:9]
	s_mov_b32 m0, s5
	s_nop 0
	global_load_lds_dwordx4 v[2:3], off
	v_lshl_add_u64 v[2:3], v[6:7], 0, s[8:9]
	s_mov_b32 m0, s33
	s_mov_b64 s[8:9], 0x20780
	global_load_lds_dwordx4 v[2:3], off
	v_lshl_add_u64 v[2:3], v[6:7], 0, s[8:9]
	s_mov_b32 m0, s38
	s_mov_b64 s[8:9], 0x40780
	global_load_lds_dwordx4 v[2:3], off
	v_lshl_add_u64 v[2:3], v[6:7], 0, s[8:9]
	s_mov_b32 m0, s39
	s_mov_b64 s[8:9], 0x60780
	global_load_lds_dwordx4 v[2:3], off
	v_lshl_add_u64 v[2:3], v[6:7], 0, s[8:9]
	s_mov_b32 m0, s56
	s_nop 0
	global_load_lds_dwordx4 v[2:3], off
	ds_read_b128 v[2:5], v10 offset:49152
	ds_read_b128 v[72:75], v10 offset:51200
	ds_read_b128 v[76:79], v10 offset:53248
	ds_read_b128 v[106:109], v10 offset:55296
	ds_read_b128 v[112:115], v13
	ds_read_b128 v[116:119], v13 offset:2048
	ds_read_b128 v[120:123], v13 offset:4096
	ds_read_b128 v[124:127], v13 offset:6144
	s_waitcnt lgkmcnt(8)
	v_mfma_f32_16x16x32_bf16 v[84:87], v[152:155], v[102:105], v[84:87]
	v_mfma_f32_16x16x32_bf16 v[88:91], v[156:159], v[102:105], v[88:91]
	v_mfma_f32_16x16x32_bf16 v[92:95], v[160:163], v[102:105], v[92:95]
	v_mfma_f32_16x16x32_bf16 v[22:25], v[164:167], v[102:105], v[22:25]
	v_mfma_f32_16x16x32_bf16 v[38:41], v[152:155], v[132:135], v[38:41]
	v_mfma_f32_16x16x32_bf16 v[46:49], v[156:159], v[132:135], v[46:49]
	v_mfma_f32_16x16x32_bf16 v[58:61], v[160:163], v[132:135], v[58:61]
	v_mfma_f32_16x16x32_bf16 v[50:53], v[164:167], v[132:135], v[50:53]
	v_mfma_f32_16x16x32_bf16 v[42:45], v[152:155], v[138:141], v[42:45]
	v_mfma_f32_16x16x32_bf16 v[62:65], v[156:159], v[138:141], v[62:65]
	v_mfma_f32_16x16x32_bf16 v[66:69], v[160:163], v[138:141], v[66:69]
	v_mfma_f32_16x16x32_bf16 v[54:57], v[164:167], v[138:141], v[54:57]
	v_mfma_f32_16x16x32_bf16 v[34:37], v[152:155], v[142:145], v[34:37]
	v_mfma_f32_16x16x32_bf16 v[30:33], v[156:159], v[142:145], v[30:33]
	v_mfma_f32_16x16x32_bf16 v[26:29], v[160:163], v[142:145], v[26:29]
	v_mfma_f32_16x16x32_bf16 v[18:21], v[164:167], v[142:145], v[18:21]
	s_waitcnt vmcnt(6) lgkmcnt(0)
	s_barrier
	ds_read_b128 v[102:105], v14
	ds_read_b128 v[128:131], v14 offset:2048
	ds_read_b128 v[132:135], v14 offset:4096
	ds_read_b128 v[138:141], v14 offset:6144
	ds_read_b128 v[142:145], v15
	ds_read_b128 v[152:155], v15 offset:2048
	ds_read_b128 v[156:159], v15 offset:4096
	ds_read_b128 v[12:15], v15 offset:6144
	v_mfma_f32_16x16x32_bf16 v[84:87], v[112:115], v[2:5], v[84:87]
	v_mfma_f32_16x16x32_bf16 v[88:91], v[116:119], v[2:5], v[88:91]
	v_mfma_f32_16x16x32_bf16 v[92:95], v[120:123], v[2:5], v[92:95]
	v_mfma_f32_16x16x32_bf16 v[2:5], v[124:127], v[2:5], v[22:25]
	v_mfma_f32_16x16x32_bf16 v[22:25], v[112:115], v[72:75], v[38:41]
	v_mfma_f32_16x16x32_bf16 v[38:41], v[116:119], v[72:75], v[46:49]
	v_mfma_f32_16x16x32_bf16 v[46:49], v[120:123], v[72:75], v[58:61]
	v_mfma_f32_16x16x32_bf16 v[50:53], v[124:127], v[72:75], v[50:53]
	v_mfma_f32_16x16x32_bf16 v[42:45], v[112:115], v[76:79], v[42:45]
	v_mfma_f32_16x16x32_bf16 v[58:61], v[116:119], v[76:79], v[62:65]
	v_mfma_f32_16x16x32_bf16 v[62:65], v[120:123], v[76:79], v[66:69]
	v_mfma_f32_16x16x32_bf16 v[54:57], v[124:127], v[76:79], v[54:57]
	v_mfma_f32_16x16x32_bf16 v[34:37], v[112:115], v[106:109], v[34:37]
	v_mfma_f32_16x16x32_bf16 v[30:33], v[116:119], v[106:109], v[30:33]
	v_mfma_f32_16x16x32_bf16 v[26:29], v[120:123], v[106:109], v[26:29]
	v_mfma_f32_16x16x32_bf16 v[18:21], v[124:127], v[106:109], v[18:21]
	ds_read_b128 v[66:69], v16
	ds_read_b128 v[72:75], v16 offset:2048
	ds_read_b128 v[76:79], v16 offset:4096
	ds_read_b128 v[106:109], v16 offset:6144
	ds_read_b128 v[112:115], v17
	ds_read_b128 v[116:119], v17 offset:2048
	ds_read_b128 v[120:123], v17 offset:4096
	ds_read_b128 v[124:127], v17 offset:6144
	s_waitcnt lgkmcnt(8)
	v_mfma_f32_16x16x32_bf16 v[84:87], v[142:145], v[102:105], v[84:87]
	v_mfma_f32_16x16x32_bf16 v[88:91], v[152:155], v[102:105], v[88:91]
	v_mfma_f32_16x16x32_bf16 v[92:95], v[156:159], v[102:105], v[92:95]
	v_mfma_f32_16x16x32_bf16 v[2:5], v[12:15], v[102:105], v[2:5]
	v_mfma_f32_16x16x32_bf16 v[22:25], v[142:145], v[128:131], v[22:25]
	v_mfma_f32_16x16x32_bf16 v[38:41], v[152:155], v[128:131], v[38:41]
	v_mfma_f32_16x16x32_bf16 v[46:49], v[156:159], v[128:131], v[46:49]
	v_mfma_f32_16x16x32_bf16 v[50:53], v[12:15], v[128:131], v[50:53]
	v_mfma_f32_16x16x32_bf16 v[42:45], v[142:145], v[132:135], v[42:45]
	v_mfma_f32_16x16x32_bf16 v[58:61], v[152:155], v[132:135], v[58:61]
	v_mfma_f32_16x16x32_bf16 v[62:65], v[156:159], v[132:135], v[62:65]
	v_mfma_f32_16x16x32_bf16 v[54:57], v[12:15], v[132:135], v[54:57]
	v_mfma_f32_16x16x32_bf16 v[34:37], v[142:145], v[138:141], v[34:37]
	v_mfma_f32_16x16x32_bf16 v[30:33], v[152:155], v[138:141], v[30:33]
	v_mfma_f32_16x16x32_bf16 v[26:29], v[156:159], v[138:141], v[26:29]
	v_mfma_f32_16x16x32_bf16 v[12:15], v[12:15], v[138:141], v[18:21]
	s_waitcnt vmcnt(0) lgkmcnt(0)
	s_barrier
	s_nop 1
	ds_read_b128 v[16:19], v8
	ds_read_b128 v[102:105], v8 offset:2048
	ds_read_b128 v[128:131], v8 offset:4096
	ds_read_b128 v[132:135], v8 offset:6144
	ds_read_b128 v[138:141], v9 offset:16384
	ds_read_b128 v[142:145], v9 offset:18432
	ds_read_b128 v[152:155], v9 offset:20480
	ds_read_b128 v[6:9], v9 offset:22528
	v_mfma_f32_16x16x32_bf16 v[84:87], v[112:115], v[66:69], v[84:87]
	v_mfma_f32_16x16x32_bf16 v[88:91], v[116:119], v[66:69], v[88:91]
	v_mfma_f32_16x16x32_bf16 v[92:95], v[120:123], v[66:69], v[92:95]
	v_mfma_f32_16x16x32_bf16 v[2:5], v[124:127], v[66:69], v[2:5]
	v_mfma_f32_16x16x32_bf16 v[20:23], v[112:115], v[72:75], v[22:25]
	v_mfma_f32_16x16x32_bf16 v[38:41], v[116:119], v[72:75], v[38:41]
	v_mfma_f32_16x16x32_bf16 v[46:49], v[120:123], v[72:75], v[46:49]
	v_mfma_f32_16x16x32_bf16 v[50:53], v[124:127], v[72:75], v[50:53]
	v_mfma_f32_16x16x32_bf16 v[42:45], v[112:115], v[76:79], v[42:45]
	v_mfma_f32_16x16x32_bf16 v[58:61], v[116:119], v[76:79], v[58:61]
	v_mfma_f32_16x16x32_bf16 v[62:65], v[120:123], v[76:79], v[62:65]
	v_mfma_f32_16x16x32_bf16 v[54:57], v[124:127], v[76:79], v[54:57]
	v_mfma_f32_16x16x32_bf16 v[34:37], v[112:115], v[106:109], v[34:37]
	v_mfma_f32_16x16x32_bf16 v[30:33], v[116:119], v[106:109], v[30:33]
	v_mfma_f32_16x16x32_bf16 v[24:27], v[120:123], v[106:109], v[26:29]
	v_mfma_f32_16x16x32_bf16 v[12:15], v[124:127], v[106:109], v[12:15]
	ds_read_b128 v[66:69], v10
	ds_read_b128 v[72:75], v10 offset:2048
	ds_read_b128 v[76:79], v10 offset:4096
	ds_read_b128 v[106:109], v10 offset:6144
	ds_read_b128 v[112:115], v11 offset:16384
	ds_read_b128 v[116:119], v11 offset:18432
	ds_read_b128 v[120:123], v11 offset:20480
	ds_read_b128 v[124:127], v11 offset:22528
	s_addk_i32 s1, 0xf700
	s_waitcnt lgkmcnt(8)
	v_mfma_f32_16x16x32_bf16 v[84:87], v[138:141], v[16:19], v[84:87]
	v_mfma_f32_16x16x32_bf16 v[88:91], v[142:145], v[16:19], v[88:91]
	v_mfma_f32_16x16x32_bf16 v[92:95], v[152:155], v[16:19], v[92:95]
	v_mfma_f32_16x16x32_bf16 v[2:5], v[6:9], v[16:19], v[2:5]
	v_mfma_f32_16x16x32_bf16 v[16:19], v[138:141], v[102:105], v[20:23]
	v_mfma_f32_16x16x32_bf16 v[20:23], v[142:145], v[102:105], v[38:41]
	v_mfma_f32_16x16x32_bf16 v[38:41], v[152:155], v[102:105], v[46:49]
	v_mfma_f32_16x16x32_bf16 v[46:49], v[6:9], v[102:105], v[50:53]
	v_mfma_f32_16x16x32_bf16 v[42:45], v[138:141], v[128:131], v[42:45]
	v_mfma_f32_16x16x32_bf16 v[50:53], v[142:145], v[128:131], v[58:61]
	v_mfma_f32_16x16x32_bf16 v[58:61], v[152:155], v[128:131], v[62:65]
	v_mfma_f32_16x16x32_bf16 v[54:57], v[6:9], v[128:131], v[54:57]
	v_mfma_f32_16x16x32_bf16 v[34:37], v[138:141], v[132:135], v[34:37]
	v_mfma_f32_16x16x32_bf16 v[28:31], v[142:145], v[132:135], v[30:33]
	v_mfma_f32_16x16x32_bf16 v[24:27], v[152:155], v[132:135], v[24:27]
	v_mfma_f32_16x16x32_bf16 v[6:9], v[6:9], v[132:135], v[12:15]
	s_waitcnt vmcnt(0) lgkmcnt(0)
	s_barrier
	v_mfma_f32_16x16x32_bf16 v[10:13], v[112:115], v[66:69], v[84:87]
	v_mfma_f32_16x16x32_bf16 v[62:65], v[116:119], v[66:69], v[88:91]
	v_mfma_f32_16x16x32_bf16 v[84:87], v[120:123], v[66:69], v[92:95]
	v_mfma_f32_16x16x32_bf16 v[2:5], v[124:127], v[66:69], v[2:5]
	v_mfma_f32_16x16x32_bf16 v[14:17], v[112:115], v[72:75], v[16:19]
	v_mfma_f32_16x16x32_bf16 v[18:21], v[116:119], v[72:75], v[20:23]
	v_mfma_f32_16x16x32_bf16 v[38:41], v[120:123], v[72:75], v[38:41]
	v_mfma_f32_16x16x32_bf16 v[46:49], v[124:127], v[72:75], v[46:49]
	v_mfma_f32_16x16x32_bf16 v[42:45], v[112:115], v[76:79], v[42:45]
	v_mfma_f32_16x16x32_bf16 v[50:53], v[116:119], v[76:79], v[50:53]
	v_mfma_f32_16x16x32_bf16 v[58:61], v[120:123], v[76:79], v[58:61]
	v_mfma_f32_16x16x32_bf16 v[54:57], v[124:127], v[76:79], v[54:57]
	v_mfma_f32_16x16x32_bf16 v[32:35], v[112:115], v[106:109], v[34:37]
	v_mfma_f32_16x16x32_bf16 v[28:31], v[116:119], v[106:109], v[28:31]
	v_mfma_f32_16x16x32_bf16 v[22:25], v[120:123], v[106:109], v[24:27]
	v_mfma_f32_16x16x32_bf16 v[6:9], v[124:127], v[106:109], v[6:9]
	v_lshlrev_b32_e32 v36, 6, v83
	v_lshlrev_b32_e32 v37, 2, v110
	s_and_b32 s0, s0, 0xf00
	v_lshl_add_u32 v26, v82, 6, s1
	v_or3_b32 v66, v36, v37, s0
	s_lshl_b32 s0, s4, 4
	v_and_b32_e32 v27, 0xc0, v26
	s_and_b32 s0, s0, 0x300
	v_or3_b32 v36, s0, v27, v101
	v_lshlrev_b32_e32 v26, 4, v26
	v_and_b32_e32 v26, 0xfffff000, v26
	v_lshlrev_b32_e32 v98, 14, v36
	v_ashrrev_i32_e32 v27, 31, v26
	v_lshl_add_u64 v[36:37], s[18:19], 0, v[98:99]
	v_lshl_add_u64 v[26:27], v[26:27], 1, v[36:37]
	v_lshlrev_b32_e32 v98, 1, v66
	v_lshl_add_u64 v[26:27], v[26:27], 0, v[98:99]
	v_cvt_pk_bf16_f32 v10, v10, v11
	v_cvt_pk_bf16_f32 v11, v12, v13
	s_waitcnt lgkmcnt(0)
	s_barrier
	global_store_dwordx2 v[26:27], v[10:11], off sc1
	v_cvt_pk_bf16_f32 v10, v62, v63
	v_cvt_pk_bf16_f32 v11, v64, v65
	global_store_dwordx2 v[26:27], v[10:11], off offset:32 sc1
	v_cvt_pk_bf16_f32 v10, v84, v85
	v_cvt_pk_bf16_f32 v11, v86, v87
	global_store_dwordx2 v[26:27], v[10:11], off offset:64 sc1
	v_add_co_u32_e32 v10, vcc, s37, v26
	v_cvt_pk_bf16_f32 v2, v2, v3
	v_cvt_pk_bf16_f32 v3, v4, v5
	v_cvt_pk_bf16_f32 v4, v14, v15
	v_cvt_pk_bf16_f32 v5, v16, v17
	v_addc_co_u32_e32 v11, vcc, 0, v27, vcc
	global_store_dwordx2 v[26:27], v[2:3], off offset:96 sc1
	v_lshl_add_u64 v[2:3], v[26:27], 0, s[68:69]
	global_store_dwordx2 v[10:11], v[4:5], off sc1
	v_cvt_pk_bf16_f32 v4, v18, v19
	v_cvt_pk_bf16_f32 v5, v20, v21
	global_store_dwordx2 v[2:3], v[4:5], off offset:32 sc1
	v_cvt_pk_bf16_f32 v4, v38, v39
	v_cvt_pk_bf16_f32 v5, v40, v41
	global_store_dwordx2 v[2:3], v[4:5], off offset:64 sc1
	v_cvt_pk_bf16_f32 v4, v46, v47
	v_cvt_pk_bf16_f32 v5, v48, v49
	v_add_co_u32_e32 v10, vcc, s65, v26
	global_store_dwordx2 v[2:3], v[4:5], off offset:96 sc1
	v_cvt_pk_bf16_f32 v4, v42, v43
	v_cvt_pk_bf16_f32 v5, v44, v45
	v_addc_co_u32_e32 v11, vcc, 0, v27, vcc
	v_lshl_add_u64 v[2:3], v[26:27], 0, s[30:31]
	global_store_dwordx2 v[10:11], v[4:5], off sc1
	v_cvt_pk_bf16_f32 v4, v50, v51
	v_cvt_pk_bf16_f32 v5, v52, v53
	global_store_dwordx2 v[2:3], v[4:5], off offset:32 sc1
	v_cvt_pk_bf16_f32 v4, v58, v59
	v_cvt_pk_bf16_f32 v5, v60, v61
	global_store_dwordx2 v[2:3], v[4:5], off offset:64 sc1
	v_cvt_pk_bf16_f32 v4, v54, v55
	v_cvt_pk_bf16_f32 v5, v56, v57
	v_add_co_u32_e32 v10, vcc, s78, v26
	global_store_dwordx2 v[2:3], v[4:5], off offset:96 sc1
	v_cvt_pk_bf16_f32 v4, v32, v33
	v_cvt_pk_bf16_f32 v5, v34, v35
	v_addc_co_u32_e32 v11, vcc, 0, v27, vcc
	v_lshl_add_u64 v[2:3], v[26:27], 0, s[24:25]
	global_store_dwordx2 v[10:11], v[4:5], off sc1
	v_cvt_pk_bf16_f32 v4, v28, v29
	v_cvt_pk_bf16_f32 v5, v30, v31
	global_store_dwordx2 v[2:3], v[4:5], off offset:32 sc1
	v_cvt_pk_bf16_f32 v4, v22, v23
	v_cvt_pk_bf16_f32 v5, v24, v25
	global_store_dwordx2 v[2:3], v[4:5], off offset:64 sc1
	v_cvt_pk_bf16_f32 v4, v6, v7
	v_cvt_pk_bf16_f32 v5, v8, v9
	global_store_dwordx2 v[2:3], v[4:5], off offset:96 sc1

.LBB0_333:
	s_waitcnt vmcnt(0)
	s_waitcnt vmcnt(0)
	s_barrier
	s_mov_b64 s[0:1], exec
	v_readlane_b32 s4, v197, 0
	v_readlane_b32 s5, v197, 1
	s_and_b64 s[4:5], s[0:1], s[4:5]
	s_xor_b64 s[0:1], s[4:5], s[0:1]
	s_mov_b64 exec, s[4:5]
	s_cbranch_execz .LBB0_335
	s_lshr_b32 s4, s58, 2
	s_and_b32 s4, s4, 12
	s_nop 0
	s_waitcnt vmcnt(0)
	v_mov_b32_e32 v2, s4
	global_atomic_add v2, v148, s[92:93] offset:128
